# fourier_combine middle output row: four serial row-quarter loads issued together with counted waits, the two VV loads share one wait
# baseline (speedup 1.0000x reference)
.LBB0_461:
	s_waitcnt lgkmcnt(0)
	global_load_dwordx4 v[8:11], v[0:1], off
	global_load_dwordx4 v[20:23], v[0:1], off offset:1024
	global_load_dwordx4 v[24:27], v[0:1], off offset:2048
	global_load_dwordx4 v[28:31], v[0:1], off offset:3072
	s_waitcnt vmcnt(3)
	v_lshlrev_b32_e32 v12, 16, v8
	v_and_b32_e32 v8, 0xffff0000, v8
	v_sub_f32_e32 v8, v12, v8
	v_lshlrev_b32_e32 v12, 16, v9
	v_and_b32_e32 v9, 0xffff0000, v9
	v_add_f32_e32 v8, 0, v8
	v_sub_f32_e32 v9, v12, v9
	v_add_f32_e32 v8, v9, v8
	v_lshlrev_b32_e32 v9, 16, v10
	v_and_b32_e32 v10, 0xffff0000, v10
	v_sub_f32_e32 v9, v9, v10
	v_add_f32_e32 v8, v9, v8
	v_lshlrev_b32_e32 v9, 16, v11
	v_and_b32_e32 v10, 0xffff0000, v11
	v_sub_f32_e32 v9, v9, v10
	v_add_f32_e32 v12, v9, v8
	s_waitcnt vmcnt(2)
	v_lshlrev_b32_e32 v13, 16, v20
	v_and_b32_e32 v8, 0xffff0000, v20
	v_sub_f32_e32 v8, v13, v8
	v_add_f32_e32 v8, v8, v12
	v_lshlrev_b32_e32 v12, 16, v21
	v_and_b32_e32 v9, 0xffff0000, v21
	v_sub_f32_e32 v9, v12, v9
	v_add_f32_e32 v8, v9, v8
	v_lshlrev_b32_e32 v9, 16, v22
	v_and_b32_e32 v10, 0xffff0000, v22
	v_sub_f32_e32 v9, v9, v10
	v_add_f32_e32 v8, v9, v8
	v_lshlrev_b32_e32 v9, 16, v23
	v_and_b32_e32 v10, 0xffff0000, v23
	v_sub_f32_e32 v9, v9, v10
	v_add_f32_e32 v12, v9, v8
	s_waitcnt vmcnt(1)
	v_lshlrev_b32_e32 v13, 16, v24
	v_and_b32_e32 v8, 0xffff0000, v24
	v_sub_f32_e32 v8, v13, v8
	v_add_f32_e32 v8, v8, v12
	v_lshlrev_b32_e32 v12, 16, v25
	v_and_b32_e32 v9, 0xffff0000, v25
	v_sub_f32_e32 v9, v12, v9
	v_add_f32_e32 v8, v9, v8
	v_lshlrev_b32_e32 v9, 16, v26
	v_and_b32_e32 v10, 0xffff0000, v26
	v_sub_f32_e32 v9, v9, v10
	v_add_f32_e32 v8, v9, v8
	v_lshlrev_b32_e32 v9, 16, v27
	v_and_b32_e32 v10, 0xffff0000, v27
	v_sub_f32_e32 v9, v9, v10
	v_add_f32_e32 v12, v9, v8
	s_waitcnt vmcnt(0)
	v_lshlrev_b32_e32 v13, 16, v28
	v_and_b32_e32 v8, 0xffff0000, v28
	v_sub_f32_e32 v8, v13, v8
	v_add_f32_e32 v8, v8, v12
	v_lshlrev_b32_e32 v12, 16, v29
	v_and_b32_e32 v9, 0xffff0000, v29
	v_sub_f32_e32 v9, v12, v9
	v_add_f32_e32 v8, v9, v8
	v_lshlrev_b32_e32 v9, 16, v30
	v_and_b32_e32 v10, 0xffff0000, v30
	v_sub_f32_e32 v9, v9, v10
	v_add_f32_e32 v8, v9, v8
	v_lshlrev_b32_e32 v9, 16, v31
	v_and_b32_e32 v10, 0xffff0000, v31
	v_sub_f32_e32 v9, v9, v10
	v_add_f32_e32 v8, v9, v8
	ds_bpermute_b32 v9, v2, v8
	s_waitcnt lgkmcnt(0)
	v_add_f32_e32 v8, v8, v9
	ds_bpermute_b32 v9, v3, v8
	s_waitcnt lgkmcnt(0)
	v_add_f32_e32 v8, v8, v9
	ds_bpermute_b32 v9, v4, v8
	s_waitcnt lgkmcnt(0)
	v_add_f32_e32 v8, v8, v9
	ds_bpermute_b32 v9, v5, v8
	s_waitcnt lgkmcnt(0)
	v_add_f32_e32 v8, v8, v9
	ds_bpermute_b32 v9, v6, v8
	s_waitcnt lgkmcnt(0)
	v_add_f32_e32 v8, v8, v9
	ds_bpermute_b32 v9, v7, v8
	s_and_saveexec_b64 s[22:23], vcc
	s_cbranch_execz .LBB0_460
	s_waitcnt lgkmcnt(0)
	v_add_f32_e32 v8, v8, v9
	v_mov_b32_e32 v9, 0x2000
	global_load_dword v9, v9, s[6:7]
	global_load_dword v10, v197, s[6:7]
	s_waitcnt vmcnt(0)
	v_add_f32_e32 v8, v8, v9
	v_add_f32_e32 v8, v8, v10
	v_mul_f32_e32 v8, 0x3c3504f3, v8
	v_bfe_u32 v9, v8, 16, 1
	v_add3_u32 v8, v8, v9, s66
	global_store_short_d16_hi v197, v8, s[14:15]
	s_branch .LBB0_460
